# code placement: the six GEMM K-loop heads aligned to 64 bytes (.p2align 6)
# baseline (speedup 1.0000x reference)
.LBB0_402:
	s_add_u32 s7, s14, 0x100
	v_mov_b32_e32 v34, 0
	s_addc_u32 s36, s15, 0
	s_mov_b32 s37, -2
	v_mov_b32_e32 v35, v34
	v_mov_b32_e32 v36, v34
	v_mov_b32_e32 v37, v34
	v_mov_b32_e32 v50, v34
	v_mov_b32_e32 v51, v34
	v_mov_b32_e32 v52, v34
	v_mov_b32_e32 v53, v34
	v_mov_b32_e32 v42, v34
	v_mov_b32_e32 v43, v34
	v_mov_b32_e32 v44, v34
	v_mov_b32_e32 v45, v34
	v_mov_b32_e32 v58, v34
	v_mov_b32_e32 v59, v34
	v_mov_b32_e32 v60, v34
	v_mov_b32_e32 v61, v34
	v_mov_b32_e32 v38, v34
	v_mov_b32_e32 v39, v34
	v_mov_b32_e32 v40, v34
	v_mov_b32_e32 v41, v34
	v_mov_b32_e32 v54, v34
	v_mov_b32_e32 v55, v34
	v_mov_b32_e32 v56, v34
	v_mov_b32_e32 v57, v34
	v_mov_b32_e32 v46, v34
	v_mov_b32_e32 v47, v34
	v_mov_b32_e32 v48, v34
	v_mov_b32_e32 v49, v34
	v_mov_b32_e32 v62, v34
	v_mov_b32_e32 v63, v34
	v_mov_b32_e32 v64, v34
	v_mov_b32_e32 v65, v34
	v_mov_b32_e32 v98, v34
	v_mov_b32_e32 v99, v34
	v_mov_b32_e32 v100, v34
	v_mov_b32_e32 v101, v34
	v_mov_b32_e32 v114, v34
	v_mov_b32_e32 v115, v34
	v_mov_b32_e32 v116, v34
	v_mov_b32_e32 v117, v34
	v_mov_b32_e32 v106, v34
	v_mov_b32_e32 v107, v34
	v_mov_b32_e32 v108, v34
	v_mov_b32_e32 v109, v34
	v_mov_b32_e32 v122, v34
	v_mov_b32_e32 v123, v34
	v_mov_b32_e32 v124, v34
	v_mov_b32_e32 v125, v34
	v_mov_b32_e32 v102, v34
	v_mov_b32_e32 v103, v34
	v_mov_b32_e32 v104, v34
	v_mov_b32_e32 v105, v34
	v_mov_b32_e32 v118, v34
	v_mov_b32_e32 v119, v34
	v_mov_b32_e32 v120, v34
	v_mov_b32_e32 v121, v34
	v_mov_b32_e32 v110, v34
	v_mov_b32_e32 v111, v34
	v_mov_b32_e32 v112, v34
	v_mov_b32_e32 v113, v34
	v_mov_b32_e32 v126, v34
	v_mov_b32_e32 v127, v34
	v_mov_b32_e32 v128, v34
	v_mov_b32_e32 v129, v34
	v_mov_b32_e32 v66, v34
	v_mov_b32_e32 v67, v34
	v_mov_b32_e32 v68, v34
	v_mov_b32_e32 v69, v34
	v_mov_b32_e32 v82, v34
	v_mov_b32_e32 v83, v34
	v_mov_b32_e32 v84, v34
	v_mov_b32_e32 v85, v34
	v_mov_b32_e32 v74, v34
	v_mov_b32_e32 v75, v34
	v_mov_b32_e32 v76, v34
	v_mov_b32_e32 v77, v34
	v_mov_b32_e32 v90, v34
	v_mov_b32_e32 v91, v34
	v_mov_b32_e32 v92, v34
	v_mov_b32_e32 v93, v34
	v_mov_b32_e32 v70, v34
	v_mov_b32_e32 v71, v34
	v_mov_b32_e32 v72, v34
	v_mov_b32_e32 v73, v34
	v_mov_b32_e32 v86, v34
	v_mov_b32_e32 v87, v34
	v_mov_b32_e32 v88, v34
	v_mov_b32_e32 v89, v34
	v_mov_b32_e32 v78, v34
	v_mov_b32_e32 v79, v34
	v_mov_b32_e32 v80, v34
	v_mov_b32_e32 v81, v34
	v_mov_b32_e32 v94, v34
	v_mov_b32_e32 v95, v34
	v_mov_b32_e32 v96, v34
	v_mov_b32_e32 v97, v34
	v_mov_b32_e32 v130, v34
	v_mov_b32_e32 v131, v34
	v_mov_b32_e32 v132, v34
	v_mov_b32_e32 v133, v34
	v_mov_b32_e32 v146, v34
	v_mov_b32_e32 v147, v34
	v_mov_b32_e32 v148, v34
	v_mov_b32_e32 v149, v34
	v_mov_b32_e32 v138, v34
	v_mov_b32_e32 v139, v34
	v_mov_b32_e32 v140, v34
	v_mov_b32_e32 v141, v34
	v_mov_b32_e32 v154, v34
	v_mov_b32_e32 v155, v34
	v_mov_b32_e32 v156, v34
	v_mov_b32_e32 v157, v34
	v_mov_b32_e32 v134, v34
	v_mov_b32_e32 v135, v34
	v_mov_b32_e32 v136, v34
	v_mov_b32_e32 v137, v34
	v_mov_b32_e32 v150, v34
	v_mov_b32_e32 v151, v34
	v_mov_b32_e32 v152, v34
	v_mov_b32_e32 v153, v34
	v_mov_b32_e32 v142, v34
	v_mov_b32_e32 v143, v34
	v_mov_b32_e32 v144, v34
	v_mov_b32_e32 v145, v34
	v_mov_b32_e32 v158, v34
	v_mov_b32_e32 v159, v34
	v_mov_b32_e32 v160, v34
	v_mov_b32_e32 v161, v34
	.p2align	6

.LBB0_939:
	s_add_u32 s1, s20, 0x100
	s_addc_u32 s3, s21, 0
	s_mov_b32 s11, -2
	.p2align	6

.LBB0_957:
	s_add_u32 s35, s12, 0x100
	v_mov_b32_e32 v0, 0
	s_addc_u32 s36, s13, 0
	s_mov_b32 s37, -2
	v_mov_b32_e32 v1, v0
	v_mov_b32_e32 v2, v0
	v_mov_b32_e32 v3, v0
	v_mov_b32_e32 v4, v0
	v_mov_b32_e32 v5, v0
	v_mov_b32_e32 v6, v0
	v_mov_b32_e32 v7, v0
	v_mov_b32_e32 v16, v0
	v_mov_b32_e32 v17, v0
	v_mov_b32_e32 v18, v0
	v_mov_b32_e32 v19, v0
	v_mov_b32_e32 v20, v0
	v_mov_b32_e32 v21, v0
	v_mov_b32_e32 v22, v0
	v_mov_b32_e32 v23, v0
	v_mov_b32_e32 v34, v0
	v_mov_b32_e32 v35, v0
	v_mov_b32_e32 v36, v0
	v_mov_b32_e32 v37, v0
	v_mov_b32_e32 v38, v0
	v_mov_b32_e32 v39, v0
	v_mov_b32_e32 v40, v0
	v_mov_b32_e32 v41, v0
	v_mov_b32_e32 v50, v0
	v_mov_b32_e32 v51, v0
	v_mov_b32_e32 v52, v0
	v_mov_b32_e32 v53, v0
	v_mov_b32_e32 v54, v0
	v_mov_b32_e32 v55, v0
	v_mov_b32_e32 v56, v0
	v_mov_b32_e32 v57, v0
	v_mov_b32_e32 v8, v0
	v_mov_b32_e32 v9, v0
	v_mov_b32_e32 v10, v0
	v_mov_b32_e32 v11, v0
	v_mov_b32_e32 v12, v0
	v_mov_b32_e32 v13, v0
	v_mov_b32_e32 v14, v0
	v_mov_b32_e32 v15, v0
	v_mov_b32_e32 v24, v0
	v_mov_b32_e32 v25, v0
	v_mov_b32_e32 v26, v0
	v_mov_b32_e32 v27, v0
	v_mov_b32_e32 v28, v0
	v_mov_b32_e32 v29, v0
	v_mov_b32_e32 v30, v0
	v_mov_b32_e32 v31, v0
	v_mov_b32_e32 v42, v0
	v_mov_b32_e32 v43, v0
	v_mov_b32_e32 v44, v0
	v_mov_b32_e32 v45, v0
	v_mov_b32_e32 v46, v0
	v_mov_b32_e32 v47, v0
	v_mov_b32_e32 v48, v0
	v_mov_b32_e32 v49, v0
	v_mov_b32_e32 v58, v0
	v_mov_b32_e32 v59, v0
	v_mov_b32_e32 v60, v0
	v_mov_b32_e32 v61, v0
	v_mov_b32_e32 v62, v0
	v_mov_b32_e32 v63, v0
	v_mov_b32_e32 v64, v0
	v_mov_b32_e32 v65, v0
	v_mov_b32_e32 v66, v0
	v_mov_b32_e32 v67, v0
	v_mov_b32_e32 v68, v0
	v_mov_b32_e32 v69, v0
	v_mov_b32_e32 v70, v0
	v_mov_b32_e32 v71, v0
	v_mov_b32_e32 v72, v0
	v_mov_b32_e32 v73, v0
	v_mov_b32_e32 v82, v0
	v_mov_b32_e32 v83, v0
	v_mov_b32_e32 v84, v0
	v_mov_b32_e32 v85, v0
	v_mov_b32_e32 v86, v0
	v_mov_b32_e32 v87, v0
	v_mov_b32_e32 v88, v0
	v_mov_b32_e32 v89, v0
	v_mov_b32_e32 v98, v0
	v_mov_b32_e32 v99, v0
	v_mov_b32_e32 v100, v0
	v_mov_b32_e32 v101, v0
	v_mov_b32_e32 v102, v0
	v_mov_b32_e32 v103, v0
	v_mov_b32_e32 v104, v0
	v_mov_b32_e32 v105, v0
	v_mov_b32_e32 v114, v0
	v_mov_b32_e32 v115, v0
	v_mov_b32_e32 v116, v0
	v_mov_b32_e32 v117, v0
	v_mov_b32_e32 v118, v0
	v_mov_b32_e32 v119, v0
	v_mov_b32_e32 v120, v0
	v_mov_b32_e32 v121, v0
	v_mov_b32_e32 v74, v0
	v_mov_b32_e32 v75, v0
	v_mov_b32_e32 v76, v0
	v_mov_b32_e32 v77, v0
	v_mov_b32_e32 v78, v0
	v_mov_b32_e32 v79, v0
	v_mov_b32_e32 v80, v0
	v_mov_b32_e32 v81, v0
	v_mov_b32_e32 v90, v0
	v_mov_b32_e32 v91, v0
	v_mov_b32_e32 v92, v0
	v_mov_b32_e32 v93, v0
	v_mov_b32_e32 v94, v0
	v_mov_b32_e32 v95, v0
	v_mov_b32_e32 v96, v0
	v_mov_b32_e32 v97, v0
	v_mov_b32_e32 v106, v0
	v_mov_b32_e32 v107, v0
	v_mov_b32_e32 v108, v0
	v_mov_b32_e32 v109, v0
	v_mov_b32_e32 v110, v0
	v_mov_b32_e32 v111, v0
	v_mov_b32_e32 v112, v0
	v_mov_b32_e32 v113, v0
	v_mov_b32_e32 v126, v0
	v_mov_b32_e32 v127, v0
	v_mov_b32_e32 v128, v0
	v_mov_b32_e32 v129, v0
	v_mov_b32_e32 v134, v0
	v_mov_b32_e32 v135, v0
	v_mov_b32_e32 v136, v0
	v_mov_b32_e32 v137, v0
	.p2align	6

.LBB0_1116:
	s_add_i32 s38, s37, -2
	s_add_u32 s39, s20, 0x100
	v_mov_b32_e32 v0, 0
	s_addc_u32 s40, s21, 0
	s_mov_b32 s22, 0
	v_mov_b32_e32 v1, v0
	v_mov_b32_e32 v2, v0
	v_mov_b32_e32 v3, v0
	v_mov_b32_e32 v4, v0
	v_mov_b32_e32 v5, v0
	v_mov_b32_e32 v6, v0
	v_mov_b32_e32 v7, v0
	v_mov_b32_e32 v16, v0
	v_mov_b32_e32 v17, v0
	v_mov_b32_e32 v18, v0
	v_mov_b32_e32 v19, v0
	v_mov_b32_e32 v20, v0
	v_mov_b32_e32 v21, v0
	v_mov_b32_e32 v22, v0
	v_mov_b32_e32 v23, v0
	v_mov_b32_e32 v34, v0
	v_mov_b32_e32 v35, v0
	v_mov_b32_e32 v36, v0
	v_mov_b32_e32 v37, v0
	v_mov_b32_e32 v38, v0
	v_mov_b32_e32 v39, v0
	v_mov_b32_e32 v40, v0
	v_mov_b32_e32 v41, v0
	v_mov_b32_e32 v50, v0
	v_mov_b32_e32 v51, v0
	v_mov_b32_e32 v52, v0
	v_mov_b32_e32 v53, v0
	v_mov_b32_e32 v54, v0
	v_mov_b32_e32 v55, v0
	v_mov_b32_e32 v56, v0
	v_mov_b32_e32 v57, v0
	v_mov_b32_e32 v8, v0
	v_mov_b32_e32 v9, v0
	v_mov_b32_e32 v10, v0
	v_mov_b32_e32 v11, v0
	v_mov_b32_e32 v12, v0
	v_mov_b32_e32 v13, v0
	v_mov_b32_e32 v14, v0
	v_mov_b32_e32 v15, v0
	v_mov_b32_e32 v24, v0
	v_mov_b32_e32 v25, v0
	v_mov_b32_e32 v26, v0
	v_mov_b32_e32 v27, v0
	v_mov_b32_e32 v28, v0
	v_mov_b32_e32 v29, v0
	v_mov_b32_e32 v30, v0
	v_mov_b32_e32 v31, v0
	v_mov_b32_e32 v42, v0
	v_mov_b32_e32 v43, v0
	v_mov_b32_e32 v44, v0
	v_mov_b32_e32 v45, v0
	v_mov_b32_e32 v46, v0
	v_mov_b32_e32 v47, v0
	v_mov_b32_e32 v48, v0
	v_mov_b32_e32 v49, v0
	v_mov_b32_e32 v58, v0
	v_mov_b32_e32 v59, v0
	v_mov_b32_e32 v60, v0
	v_mov_b32_e32 v61, v0
	v_mov_b32_e32 v62, v0
	v_mov_b32_e32 v63, v0
	v_mov_b32_e32 v64, v0
	v_mov_b32_e32 v65, v0
	v_mov_b32_e32 v66, v0
	v_mov_b32_e32 v67, v0
	v_mov_b32_e32 v68, v0
	v_mov_b32_e32 v69, v0
	v_mov_b32_e32 v70, v0
	v_mov_b32_e32 v71, v0
	v_mov_b32_e32 v72, v0
	v_mov_b32_e32 v73, v0
	v_mov_b32_e32 v90, v0
	v_mov_b32_e32 v91, v0
	v_mov_b32_e32 v92, v0
	v_mov_b32_e32 v93, v0
	v_mov_b32_e32 v98, v0
	v_mov_b32_e32 v99, v0
	v_mov_b32_e32 v100, v0
	v_mov_b32_e32 v101, v0
	v_mov_b32_e32 v114, v0
	v_mov_b32_e32 v115, v0
	v_mov_b32_e32 v116, v0
	v_mov_b32_e32 v117, v0
	v_mov_b32_e32 v118, v0
	v_mov_b32_e32 v119, v0
	v_mov_b32_e32 v120, v0
	v_mov_b32_e32 v121, v0
	v_mov_b32_e32 v138, v0
	v_mov_b32_e32 v139, v0
	v_mov_b32_e32 v140, v0
	v_mov_b32_e32 v141, v0
	v_mov_b32_e32 v146, v0
	v_mov_b32_e32 v147, v0
	v_mov_b32_e32 v148, v0
	v_mov_b32_e32 v149, v0
	v_mov_b32_e32 v74, v0
	v_mov_b32_e32 v75, v0
	v_mov_b32_e32 v76, v0
	v_mov_b32_e32 v77, v0
	v_mov_b32_e32 v82, v0
	v_mov_b32_e32 v83, v0
	v_mov_b32_e32 v84, v0
	v_mov_b32_e32 v85, v0
	v_mov_b32_e32 v106, v0
	v_mov_b32_e32 v107, v0
	v_mov_b32_e32 v108, v0
	v_mov_b32_e32 v109, v0
	v_mov_b32_e32 v110, v0
	v_mov_b32_e32 v111, v0
	v_mov_b32_e32 v112, v0
	v_mov_b32_e32 v113, v0
	v_mov_b32_e32 v142, v0
	v_mov_b32_e32 v143, v0
	v_mov_b32_e32 v144, v0
	v_mov_b32_e32 v145, v0
	v_mov_b32_e32 v150, v0
	v_mov_b32_e32 v151, v0
	v_mov_b32_e32 v152, v0
	v_mov_b32_e32 v153, v0
	v_mov_b32_e32 v162, v0
	v_mov_b32_e32 v163, v0
	v_mov_b32_e32 v164, v0
	v_mov_b32_e32 v165, v0
	v_mov_b32_e32 v166, v0
	v_mov_b32_e32 v167, v0
	v_mov_b32_e32 v168, v0
	v_mov_b32_e32 v169, v0
	.p2align	6

.LBB0_1275:
	s_add_u32 s3, s16, 0x100
	v_mov_b32_e32 v0, 0
	s_addc_u32 s37, s17, 0
	s_mov_b32 s38, -2
	v_mov_b32_e32 v1, v0
	v_mov_b32_e32 v2, v0
	v_mov_b32_e32 v3, v0
	v_mov_b32_e32 v4, v0
	v_mov_b32_e32 v5, v0
	v_mov_b32_e32 v6, v0
	v_mov_b32_e32 v7, v0
	v_mov_b32_e32 v16, v0
	v_mov_b32_e32 v17, v0
	v_mov_b32_e32 v18, v0
	v_mov_b32_e32 v19, v0
	v_mov_b32_e32 v20, v0
	v_mov_b32_e32 v21, v0
	v_mov_b32_e32 v22, v0
	v_mov_b32_e32 v23, v0
	v_mov_b32_e32 v34, v0
	v_mov_b32_e32 v35, v0
	v_mov_b32_e32 v36, v0
	v_mov_b32_e32 v37, v0
	v_mov_b32_e32 v38, v0
	v_mov_b32_e32 v39, v0
	v_mov_b32_e32 v40, v0
	v_mov_b32_e32 v41, v0
	v_mov_b32_e32 v50, v0
	v_mov_b32_e32 v51, v0
	v_mov_b32_e32 v52, v0
	v_mov_b32_e32 v53, v0
	v_mov_b32_e32 v54, v0
	v_mov_b32_e32 v55, v0
	v_mov_b32_e32 v56, v0
	v_mov_b32_e32 v57, v0
	v_mov_b32_e32 v8, v0
	v_mov_b32_e32 v9, v0
	v_mov_b32_e32 v10, v0
	v_mov_b32_e32 v11, v0
	v_mov_b32_e32 v12, v0
	v_mov_b32_e32 v13, v0
	v_mov_b32_e32 v14, v0
	v_mov_b32_e32 v15, v0
	v_mov_b32_e32 v24, v0
	v_mov_b32_e32 v25, v0
	v_mov_b32_e32 v26, v0
	v_mov_b32_e32 v27, v0
	v_mov_b32_e32 v28, v0
	v_mov_b32_e32 v29, v0
	v_mov_b32_e32 v30, v0
	v_mov_b32_e32 v31, v0
	v_mov_b32_e32 v42, v0
	v_mov_b32_e32 v43, v0
	v_mov_b32_e32 v44, v0
	v_mov_b32_e32 v45, v0
	v_mov_b32_e32 v46, v0
	v_mov_b32_e32 v47, v0
	v_mov_b32_e32 v48, v0
	v_mov_b32_e32 v49, v0
	v_mov_b32_e32 v58, v0
	v_mov_b32_e32 v59, v0
	v_mov_b32_e32 v60, v0
	v_mov_b32_e32 v61, v0
	v_mov_b32_e32 v62, v0
	v_mov_b32_e32 v63, v0
	v_mov_b32_e32 v64, v0
	v_mov_b32_e32 v65, v0
	v_mov_b32_e32 v66, v0
	v_mov_b32_e32 v67, v0
	v_mov_b32_e32 v68, v0
	v_mov_b32_e32 v69, v0
	v_mov_b32_e32 v70, v0
	v_mov_b32_e32 v71, v0
	v_mov_b32_e32 v72, v0
	v_mov_b32_e32 v73, v0
	v_mov_b32_e32 v82, v0
	v_mov_b32_e32 v83, v0
	v_mov_b32_e32 v84, v0
	v_mov_b32_e32 v85, v0
	v_mov_b32_e32 v86, v0
	v_mov_b32_e32 v87, v0
	v_mov_b32_e32 v88, v0
	v_mov_b32_e32 v89, v0
	v_mov_b32_e32 v98, v0
	v_mov_b32_e32 v99, v0
	v_mov_b32_e32 v100, v0
	v_mov_b32_e32 v101, v0
	v_mov_b32_e32 v102, v0
	v_mov_b32_e32 v103, v0
	v_mov_b32_e32 v104, v0
	v_mov_b32_e32 v105, v0
	v_mov_b32_e32 v114, v0
	v_mov_b32_e32 v115, v0
	v_mov_b32_e32 v116, v0
	v_mov_b32_e32 v117, v0
	v_mov_b32_e32 v118, v0
	v_mov_b32_e32 v119, v0
	v_mov_b32_e32 v120, v0
	v_mov_b32_e32 v121, v0
	v_mov_b32_e32 v74, v0
	v_mov_b32_e32 v75, v0
	v_mov_b32_e32 v76, v0
	v_mov_b32_e32 v77, v0
	v_mov_b32_e32 v78, v0
	v_mov_b32_e32 v79, v0
	v_mov_b32_e32 v80, v0
	v_mov_b32_e32 v81, v0
	v_mov_b32_e32 v90, v0
	v_mov_b32_e32 v91, v0
	v_mov_b32_e32 v92, v0
	v_mov_b32_e32 v93, v0
	v_mov_b32_e32 v94, v0
	v_mov_b32_e32 v95, v0
	v_mov_b32_e32 v96, v0
	v_mov_b32_e32 v97, v0
	v_mov_b32_e32 v106, v0
	v_mov_b32_e32 v107, v0
	v_mov_b32_e32 v108, v0
	v_mov_b32_e32 v109, v0
	v_mov_b32_e32 v110, v0
	v_mov_b32_e32 v111, v0
	v_mov_b32_e32 v112, v0
	v_mov_b32_e32 v113, v0
	v_mov_b32_e32 v122, v0
	v_mov_b32_e32 v123, v0
	v_mov_b32_e32 v124, v0
	v_mov_b32_e32 v125, v0
	v_mov_b32_e32 v126, v0
	v_mov_b32_e32 v127, v0
	v_mov_b32_e32 v128, v0
	v_mov_b32_e32 v129, v0
	.p2align	6

.LBB0_1364:
	s_add_i32 s43, s42, -2
	s_add_u32 s44, s12, 0x100
	v_mov_b32_e32 v0, 0
	s_addc_u32 s45, s13, 0
	s_mov_b32 s14, 0
	v_mov_b32_e32 v1, v0
	v_mov_b32_e32 v2, v0
	v_mov_b32_e32 v3, v0
	v_mov_b32_e32 v4, v0
	v_mov_b32_e32 v5, v0
	v_mov_b32_e32 v6, v0
	v_mov_b32_e32 v7, v0
	v_mov_b32_e32 v16, v0
	v_mov_b32_e32 v17, v0
	v_mov_b32_e32 v18, v0
	v_mov_b32_e32 v19, v0
	v_mov_b32_e32 v20, v0
	v_mov_b32_e32 v21, v0
	v_mov_b32_e32 v22, v0
	v_mov_b32_e32 v23, v0
	v_mov_b32_e32 v34, v0
	v_mov_b32_e32 v35, v0
	v_mov_b32_e32 v36, v0
	v_mov_b32_e32 v37, v0
	v_mov_b32_e32 v38, v0
	v_mov_b32_e32 v39, v0
	v_mov_b32_e32 v40, v0
	v_mov_b32_e32 v41, v0
	v_mov_b32_e32 v50, v0
	v_mov_b32_e32 v51, v0
	v_mov_b32_e32 v52, v0
	v_mov_b32_e32 v53, v0
	v_mov_b32_e32 v54, v0
	v_mov_b32_e32 v55, v0
	v_mov_b32_e32 v56, v0
	v_mov_b32_e32 v57, v0
	v_mov_b32_e32 v8, v0
	v_mov_b32_e32 v9, v0
	v_mov_b32_e32 v10, v0
	v_mov_b32_e32 v11, v0
	v_mov_b32_e32 v12, v0
	v_mov_b32_e32 v13, v0
	v_mov_b32_e32 v14, v0
	v_mov_b32_e32 v15, v0
	v_mov_b32_e32 v24, v0
	v_mov_b32_e32 v25, v0
	v_mov_b32_e32 v26, v0
	v_mov_b32_e32 v27, v0
	v_mov_b32_e32 v28, v0
	v_mov_b32_e32 v29, v0
	v_mov_b32_e32 v30, v0
	v_mov_b32_e32 v31, v0
	v_mov_b32_e32 v42, v0
	v_mov_b32_e32 v43, v0
	v_mov_b32_e32 v44, v0
	v_mov_b32_e32 v45, v0
	v_mov_b32_e32 v46, v0
	v_mov_b32_e32 v47, v0
	v_mov_b32_e32 v48, v0
	v_mov_b32_e32 v49, v0
	v_mov_b32_e32 v58, v0
	v_mov_b32_e32 v59, v0
	v_mov_b32_e32 v60, v0
	v_mov_b32_e32 v61, v0
	v_mov_b32_e32 v62, v0
	v_mov_b32_e32 v63, v0
	v_mov_b32_e32 v64, v0
	v_mov_b32_e32 v65, v0
	v_mov_b32_e32 v66, v0
	v_mov_b32_e32 v67, v0
	v_mov_b32_e32 v68, v0
	v_mov_b32_e32 v69, v0
	v_mov_b32_e32 v70, v0
	v_mov_b32_e32 v71, v0
	v_mov_b32_e32 v72, v0
	v_mov_b32_e32 v73, v0
	v_mov_b32_e32 v82, v0
	v_mov_b32_e32 v83, v0
	v_mov_b32_e32 v84, v0
	v_mov_b32_e32 v85, v0
	v_mov_b32_e32 v86, v0
	v_mov_b32_e32 v87, v0
	v_mov_b32_e32 v88, v0
	v_mov_b32_e32 v89, v0
	v_mov_b32_e32 v98, v0
	v_mov_b32_e32 v99, v0
	v_mov_b32_e32 v100, v0
	v_mov_b32_e32 v101, v0
	v_mov_b32_e32 v102, v0
	v_mov_b32_e32 v103, v0
	v_mov_b32_e32 v104, v0
	v_mov_b32_e32 v105, v0
	v_mov_b32_e32 v118, v0
	v_mov_b32_e32 v119, v0
	v_mov_b32_e32 v120, v0
	v_mov_b32_e32 v121, v0
	v_mov_b32_e32 v126, v0
	v_mov_b32_e32 v127, v0
	v_mov_b32_e32 v128, v0
	v_mov_b32_e32 v129, v0
	v_mov_b32_e32 v74, v0
	v_mov_b32_e32 v75, v0
	v_mov_b32_e32 v76, v0
	v_mov_b32_e32 v77, v0
	v_mov_b32_e32 v78, v0
	v_mov_b32_e32 v79, v0
	v_mov_b32_e32 v80, v0
	v_mov_b32_e32 v81, v0
	v_mov_b32_e32 v90, v0
	v_mov_b32_e32 v91, v0
	v_mov_b32_e32 v92, v0
	v_mov_b32_e32 v93, v0
	v_mov_b32_e32 v94, v0
	v_mov_b32_e32 v95, v0
	v_mov_b32_e32 v96, v0
	v_mov_b32_e32 v97, v0
	v_mov_b32_e32 v122, v0
	v_mov_b32_e32 v123, v0
	v_mov_b32_e32 v124, v0
	v_mov_b32_e32 v125, v0
	v_mov_b32_e32 v130, v0
	v_mov_b32_e32 v131, v0
	v_mov_b32_e32 v132, v0
	v_mov_b32_e32 v133, v0
	v_mov_b32_e32 v142, v0
	v_mov_b32_e32 v143, v0
	v_mov_b32_e32 v144, v0
	v_mov_b32_e32 v145, v0
	v_mov_b32_e32 v146, v0
	v_mov_b32_e32 v147, v0
	v_mov_b32_e32 v148, v0
	v_mov_b32_e32 v149, v0
	.p2align	6
